# FFN1-down: slice-owning workgroups run their context K-slice unit before the latent unit (unit-index bijection), staggering the epilogue burst
# speedup vs baseline: 1.0156x; 1.0156x over previous
.LBB0_292:
	s_cmp_gt_u32 s76, 256
	s_cbranch_scc1 .Lrm1_p_done
	s_cmp_lt_u32 s75, 176
	s_cbranch_scc0 .Lrm1_p_done
	s_mul_hi_u32 s84, s75, 0xba2e8ba3
	s_lshr_b32 s84, s84, 3
	s_mul_i32 s85, s84, 11
	s_sub_u32 s85, s75, s85
	s_lshr_b32 s68, s84, 2
	s_add_u32 s68, s68, 64
	s_and_b32 s69, s84, 3
	s_lshl_b32 s6, s85, 2
	s_mov_b32 s70, 4

.LBB0_298:
	s_add_i32 s64, s64, 1
	v_readlane_b32 s4, v253, 10
	s_mul_i32 s4, s64, s4
	s_mul_hi_u32 s5, s64, s76
	s_add_i32 s5, s5, s4
	s_mul_i32 s4, s64, s76
	s_add_u32 s8, s4, s75
	v_readlane_b32 s4, v253, 9
	s_addc_u32 s9, s5, s4
	s_cmp_gt_u32 s76, 256
	s_cbranch_scc1 .Lrm1_done
	s_cmp_lg_u32 s9, 0
	s_cbranch_scc1 .Lrm1_done
	s_cmp_ge_u32 s8, 432
	s_cbranch_scc1 .Lrm1_done
	s_cmp_lt_u32 s8, 176
	s_cbranch_scc1 .Lrm1_add
	s_cmp_lt_u32 s8, 256
	s_cbranch_scc1 .Lrm1_done
	s_sub_u32 s8, s8, 256
	s_branch .Lrm1_done
.Lrm1_add:
	s_add_u32 s8, s8, 256
.Lrm1_done:
	s_waitcnt lgkmcnt(0)
	v_mov_b64_e32 v[2:3], 0x1b0
	v_cmp_lt_i64_e64 s[4:5], s[8:9], v[2:3]
	v_mov_b64_e32 v[2:3], 0x1af
	v_cmp_gt_i64_e32 vcc, s[8:9], v[2:3]
	s_cbranch_vccnz .LBB0_307
	v_cmp_lt_i64_e32 vcc, s[8:9], v[146:147]
	s_mov_b64 s[28:29], -1
	s_cbranch_vccnz .LBB0_301
	s_add_i32 s7, s8, 0xffffff00
	s_mul_hi_i32 s9, s7, 0x2e8ba2e9
	s_ashr_i32 s26, s9, 1
	s_lshr_b32 s27, s9, 31
	s_ashr_i32 s9, s9, 3
	s_add_i32 s26, s26, s27
	s_add_i32 s9, s9, s27
	s_add_i32 s65, s9, 64
	s_ashr_i32 s9, s26, 31
	s_lshr_b32 s9, s9, 30
	s_mul_i32 s28, s26, 11
	s_add_i32 s9, s26, s9
	s_sub_i32 s7, s7, s28
	s_and_b32 s9, s9, -4
	s_sub_i32 s66, s26, s9
	s_lshl_b32 s26, s7, 2
	s_mov_b64 s[28:29], 0
